# full stack: v21 + MLA half-stagger (8-slot V ring) + EpiProj gain hoist + out-proj EpiResid epilogue rewritten with hoisted loads
# speedup vs baseline: 1.0046x; 1.0046x over previous
.LBB0_598:
	s_andn2_b64 vcc, exec, s[16:17]
	s_cbranch_vccnz .LBB0_600
	v_mov_b32_e32 v154, v125
	v_mov_b32_e32 v155, v117
	v_mov_b32_e32 v142, v124
	v_mov_b32_e32 v143, v116
	v_pk_mul_f32 v[154:155], v[154:155], v[154:155]
	v_mov_b32_e32 v156, v127
	v_mov_b32_e32 v157, v119
	v_pk_fma_f32 v[142:143], v[142:143], v[142:143], v[154:155]
	v_mov_b32_e32 v154, v126
	v_mov_b32_e32 v155, v118
	v_pk_mul_f32 v[156:157], v[156:157], v[156:157]
	v_mov_b32_e32 v160, v123
	v_pk_fma_f32 v[154:155], v[154:155], v[154:155], v[156:157]
	v_mov_b32_e32 v156, v121
	v_mov_b32_e32 v157, v113
	v_pk_add_f32 v[142:143], v[142:143], v[154:155]
	v_mov_b32_e32 v154, v120
	v_mov_b32_e32 v155, v112
	v_pk_mul_f32 v[156:157], v[156:157], v[156:157]
	v_mov_b32_e32 v161, v115
	v_pk_fma_f32 v[154:155], v[154:155], v[154:155], v[156:157]
	v_mov_b32_e32 v156, v122
	v_mov_b32_e32 v157, v114
	v_pk_mul_f32 v[160:161], v[160:161], v[160:161]
	s_mov_b64 s[54:55], s[92:93]
	v_pk_fma_f32 v[156:157], v[156:157], v[156:157], v[160:161]
	v_readlane_b32 s92, v253, 61
	v_pk_add_f32 v[154:155], v[154:155], v[156:157]
	s_and_b64 s[16:17], s[10:11], exec
	v_pk_add_f32 v[142:143], v[142:143], v[154:155]
	v_readlane_b32 s93, v253, 62
	v_add_f32_e32 v141, v142, v143
	v_and_b32_e32 v143, 64, v210
	v_xor_b32_e32 v142, 16, v210
	v_add_u32_e32 v143, 64, v143
	v_cmp_lt_i32_e32 vcc, v142, v143
	v_readlane_b32 s94, v253, 63
	v_readlane_b32 s95, v254, 0
	v_cndmask_b32_e32 v142, v210, v142, vcc
	v_lshlrev_b32_e32 v142, 2, v142
	ds_bpermute_b32 v142, v142, v141
	s_cselect_b32 s17, s93, s95
	s_cselect_b32 s16, s92, s94
	s_mov_b64 s[92:93], s[54:55]
	s_cselect_b32 s55, s62, s64
	s_waitcnt lgkmcnt(0)
	v_add_f32_e32 v141, v141, v142
	v_xor_b32_e32 v142, 32, v210
	v_cmp_lt_i32_e32 vcc, v142, v143
	s_cselect_b32 s54, s61, s63
	v_lshlrev_b32_e32 v148, 1, v146
	v_cndmask_b32_e32 v142, v210, v142, vcc
	v_lshlrev_b32_e32 v142, 2, v142
	ds_bpermute_b32 v142, v142, v141
	s_waitcnt lgkmcnt(0)
	v_add_f32_e32 v141, v141, v142
	v_fmamk_f32 v141, v141, 0x3c800000, v207
	v_rsq_f32_e32 v141, v141
	s_nop 0
	v_mul_f32_e32 v142, v147, v141
	v_ashrrev_i32_e32 v141, 31, v140
	v_lshlrev_b64 v[154:155], 10, v[140:141]
	v_lshlrev_b32_e32 v141, 2, v146
	global_load_dwordx4 v[232:235], v141, s[16:17]
	global_load_dwordx4 v[236:239], v141, s[16:17] offset:16
	global_load_dwordx4 v[240:243], v141, s[16:17] offset:128
	global_load_dwordx4 v[244:247], v141, s[16:17] offset:144
	s_waitcnt vmcnt(0)
	v_mov_b32_e32 v160, v236
	v_mov_b32_e32 v161, v237
	v_mov_b32_e32 v162, v238
	v_mov_b32_e32 v163, v239
	v_mov_b32_e32 v164, v232
	v_mov_b32_e32 v165, v233
	v_mov_b32_e32 v166, v234
	v_mov_b32_e32 v167, v235
	v_pk_mul_f32 v[156:157], v[124:125], v[142:143] op_sel_hi:[1,0]
	v_pk_mul_f32 v[168:169], v[126:127], v[142:143] op_sel_hi:[1,0]
	v_lshl_add_u64 v[154:155], s[54:55], 0, v[154:155]
	v_lshl_add_u64 v[154:155], s[46:47], 1, v[154:155]
	v_lshl_add_u64 v[154:155], v[154:155], 0, v[148:149]
	v_pk_mul_f32 v[166:167], v[166:167], v[168:169]
	v_pk_mul_f32 v[156:157], v[164:165], v[156:157]
	v_pk_mul_f32 v[164:165], v[120:121], v[142:143] op_sel_hi:[1,0]
	v_pk_mul_f32 v[168:169], v[122:123], v[142:143] op_sel_hi:[1,0]
	s_nop 0
	v_pk_mul_f32 v[168:169], v[162:163], v[168:169]
	v_pk_mul_f32 v[162:163], v[160:161], v[164:165]
	v_cvt_pk_bf16_f32 v160, v156, v157
	v_cvt_pk_bf16_f32 v161, v166, v167
	v_cvt_pk_bf16_f32 v162, v162, v163
	v_cvt_pk_bf16_f32 v163, v168, v169
	global_store_dwordx4 v[154:155], v[160:163], off
	s_nop 1
	v_mov_b32_e32 v160, v244
	v_mov_b32_e32 v161, v245
	v_mov_b32_e32 v162, v246
	v_mov_b32_e32 v163, v247
	v_mov_b32_e32 v164, v240
	v_mov_b32_e32 v165, v241
	v_mov_b32_e32 v166, v242
	v_mov_b32_e32 v167, v243
	v_pk_mul_f32 v[156:157], v[116:117], v[142:143] op_sel_hi:[1,0]
	v_pk_mul_f32 v[168:169], v[118:119], v[142:143] op_sel_hi:[1,0]
	v_pk_mul_f32 v[156:157], v[164:165], v[156:157]
	v_pk_mul_f32 v[164:165], v[112:113], v[142:143] op_sel_hi:[1,0]
	v_pk_mul_f32 v[142:143], v[114:115], v[142:143] op_sel_hi:[1,0]
	v_pk_mul_f32 v[166:167], v[166:167], v[168:169]
	v_pk_mul_f32 v[142:143], v[162:163], v[142:143]
	v_pk_mul_f32 v[162:163], v[160:161], v[164:165]
	v_cvt_pk_bf16_f32 v160, v156, v157
	v_cvt_pk_bf16_f32 v161, v166, v167
	v_cvt_pk_bf16_f32 v162, v162, v163
	v_cvt_pk_bf16_f32 v163, v142, v143
	global_store_dwordx4 v[154:155], v[160:163], off offset:64

.LBB0_617:
	s_andn2_b64 vcc, exec, s[52:53]
	s_cbranch_vccnz .LBB0_619
	v_mov_b32_e32 v116, v109
	v_mov_b32_e32 v117, v101
	v_mov_b32_e32 v114, v108
	v_mov_b32_e32 v115, v100
	v_pk_mul_f32 v[116:117], v[116:117], v[116:117]
	v_mov_b32_e32 v118, v111
	v_mov_b32_e32 v119, v103
	v_pk_fma_f32 v[114:115], v[114:115], v[114:115], v[116:117]
	v_mov_b32_e32 v116, v110
	v_mov_b32_e32 v117, v102
	v_pk_mul_f32 v[118:119], v[118:119], v[118:119]
	v_mov_b32_e32 v120, v107
	v_pk_fma_f32 v[116:117], v[116:117], v[116:117], v[118:119]
	v_mov_b32_e32 v118, v113
	v_mov_b32_e32 v119, v105
	v_pk_add_f32 v[114:115], v[114:115], v[116:117]
	v_mov_b32_e32 v116, v112
	v_mov_b32_e32 v117, v104
	v_pk_mul_f32 v[118:119], v[118:119], v[118:119]
	v_mov_b32_e32 v121, v99
	v_pk_fma_f32 v[116:117], v[116:117], v[116:117], v[118:119]
	v_mov_b32_e32 v118, v106
	v_mov_b32_e32 v119, v98
	v_pk_mul_f32 v[120:121], v[120:121], v[120:121]
	s_and_b64 s[52:53], s[10:11], exec
	v_pk_fma_f32 v[118:119], v[118:119], v[118:119], v[120:121]
	v_readlane_b32 s52, v253, 61
	v_pk_add_f32 v[116:117], v[116:117], v[118:119]
	v_readlane_b32 s53, v253, 62
	v_pk_add_f32 v[114:115], v[114:115], v[116:117]
	v_readlane_b32 s54, v253, 63
	v_add_f32_e32 v97, v114, v115
	v_and_b32_e32 v115, 64, v210
	v_xor_b32_e32 v114, 16, v210
	v_add_u32_e32 v115, 64, v115
	v_cmp_lt_i32_e32 vcc, v114, v115
	v_readlane_b32 s55, v254, 0
	s_cselect_b32 s53, s53, s55
	v_cndmask_b32_e32 v114, v210, v114, vcc
	v_lshlrev_b32_e32 v114, 2, v114
	ds_bpermute_b32 v114, v114, v97
	s_cselect_b32 s52, s52, s54
	s_cselect_b32 s55, s62, s64
	s_cselect_b32 s54, s61, s63
	v_lshlrev_b32_e32 v148, 1, v146
	s_waitcnt lgkmcnt(0)
	v_add_f32_e32 v97, v97, v114
	v_xor_b32_e32 v114, 32, v210
	v_cmp_lt_i32_e32 vcc, v114, v115
	s_nop 1
	v_cndmask_b32_e32 v114, v210, v114, vcc
	v_lshlrev_b32_e32 v114, 2, v114
	ds_bpermute_b32 v114, v114, v97
	s_waitcnt lgkmcnt(0)
	v_add_f32_e32 v97, v97, v114
	v_fmamk_f32 v97, v97, 0x3c800000, v207
	v_rsq_f32_e32 v97, v97
	s_nop 0
	v_mul_f32_e32 v114, v147, v97
	v_ashrrev_i32_e32 v97, 31, v96
	v_lshlrev_b64 v[116:117], 10, v[96:97]
	v_lshl_add_u64 v[116:117], s[54:55], 0, v[116:117]
	v_lshlrev_b32_e32 v97, 2, v146
	v_lshl_add_u64 v[124:125], s[46:47], 1, v[116:117]
	s_nop 1
	v_mov_b32_e32 v116, v236
	v_mov_b32_e32 v117, v237
	v_mov_b32_e32 v118, v238
	v_mov_b32_e32 v119, v239
	v_mov_b32_e32 v120, v232
	v_mov_b32_e32 v121, v233
	v_mov_b32_e32 v122, v234
	v_mov_b32_e32 v123, v235
	v_pk_mul_f32 v[126:127], v[108:109], v[114:115] op_sel_hi:[1,0]
	v_pk_mul_f32 v[142:143], v[110:111], v[114:115] op_sel_hi:[1,0]
	v_lshl_add_u64 v[124:125], v[124:125], 0, v[148:149]
	v_pk_mul_f32 v[122:123], v[122:123], v[142:143]
	v_pk_mul_f32 v[120:121], v[120:121], v[126:127]
	v_pk_mul_f32 v[126:127], v[112:113], v[114:115] op_sel_hi:[1,0]
	v_pk_mul_f32 v[142:143], v[106:107], v[114:115] op_sel_hi:[1,0]
	s_nop 0
	v_pk_mul_f32 v[142:143], v[118:119], v[142:143]
	v_pk_mul_f32 v[118:119], v[116:117], v[126:127]
	v_cvt_pk_bf16_f32 v116, v120, v121
	v_cvt_pk_bf16_f32 v117, v122, v123
	v_cvt_pk_bf16_f32 v118, v118, v119
	v_cvt_pk_bf16_f32 v119, v142, v143
	global_store_dwordx4 v[124:125], v[116:119], off
	s_nop 1
	v_mov_b32_e32 v116, v244
	v_mov_b32_e32 v117, v245
	v_mov_b32_e32 v118, v246
	v_mov_b32_e32 v119, v247
	v_mov_b32_e32 v120, v240
	v_mov_b32_e32 v121, v241
	v_mov_b32_e32 v122, v242
	v_mov_b32_e32 v123, v243
	v_pk_mul_f32 v[126:127], v[100:101], v[114:115] op_sel_hi:[1,0]
	v_pk_mul_f32 v[142:143], v[102:103], v[114:115] op_sel_hi:[1,0]
	v_pk_mul_f32 v[120:121], v[120:121], v[126:127]
	v_pk_mul_f32 v[126:127], v[104:105], v[114:115] op_sel_hi:[1,0]
	v_pk_mul_f32 v[114:115], v[98:99], v[114:115] op_sel_hi:[1,0]
	v_pk_mul_f32 v[122:123], v[122:123], v[142:143]
	v_pk_mul_f32 v[118:119], v[118:119], v[114:115]
	v_pk_mul_f32 v[116:117], v[116:117], v[126:127]
	v_cvt_pk_bf16_f32 v114, v120, v121
	v_cvt_pk_bf16_f32 v115, v122, v123
	v_cvt_pk_bf16_f32 v116, v116, v117
	v_cvt_pk_bf16_f32 v117, v118, v119
	global_store_dwordx4 v[124:125], v[114:117], off offset:64

.LBB0_636:
	s_andn2_b64 vcc, exec, s[52:53]
	s_cbranch_vccnz .LBB0_638
	v_mov_b32_e32 v100, v93
	v_mov_b32_e32 v101, v85
	v_mov_b32_e32 v98, v92
	v_mov_b32_e32 v99, v84
	v_pk_mul_f32 v[100:101], v[100:101], v[100:101]
	v_mov_b32_e32 v102, v95
	v_mov_b32_e32 v103, v87
	v_pk_fma_f32 v[98:99], v[98:99], v[98:99], v[100:101]
	v_mov_b32_e32 v100, v94
	v_mov_b32_e32 v101, v86
	v_pk_mul_f32 v[102:103], v[102:103], v[102:103]
	v_mov_b32_e32 v104, v91
	v_pk_fma_f32 v[100:101], v[100:101], v[100:101], v[102:103]
	v_mov_b32_e32 v102, v97
	v_mov_b32_e32 v103, v89
	v_pk_add_f32 v[98:99], v[98:99], v[100:101]
	v_mov_b32_e32 v100, v96
	v_mov_b32_e32 v101, v88
	v_pk_mul_f32 v[102:103], v[102:103], v[102:103]
	v_mov_b32_e32 v105, v83
	v_pk_fma_f32 v[100:101], v[100:101], v[100:101], v[102:103]
	v_mov_b32_e32 v102, v90
	v_mov_b32_e32 v103, v82
	v_pk_mul_f32 v[104:105], v[104:105], v[104:105]
	s_and_b64 s[52:53], s[10:11], exec
	v_pk_fma_f32 v[102:103], v[102:103], v[102:103], v[104:105]
	v_readlane_b32 s52, v253, 61
	v_pk_add_f32 v[100:101], v[100:101], v[102:103]
	v_readlane_b32 s53, v253, 62
	v_pk_add_f32 v[98:99], v[98:99], v[100:101]
	v_readlane_b32 s54, v253, 63
	v_add_f32_e32 v81, v98, v99
	v_and_b32_e32 v99, 64, v210
	v_xor_b32_e32 v98, 16, v210
	v_add_u32_e32 v99, 64, v99
	v_cmp_lt_i32_e32 vcc, v98, v99
	v_readlane_b32 s55, v254, 0
	s_cselect_b32 s53, s53, s55
	v_cndmask_b32_e32 v98, v210, v98, vcc
	v_lshlrev_b32_e32 v98, 2, v98
	ds_bpermute_b32 v98, v98, v81
	s_cselect_b32 s52, s52, s54
	s_cselect_b32 s55, s62, s64
	s_cselect_b32 s54, s61, s63
	v_lshlrev_b32_e32 v148, 1, v146
	s_waitcnt lgkmcnt(0)
	v_add_f32_e32 v81, v81, v98
	v_xor_b32_e32 v98, 32, v210
	v_cmp_lt_i32_e32 vcc, v98, v99
	s_nop 1
	v_cndmask_b32_e32 v98, v210, v98, vcc
	v_lshlrev_b32_e32 v98, 2, v98
	ds_bpermute_b32 v98, v98, v81
	s_waitcnt lgkmcnt(0)
	v_add_f32_e32 v81, v81, v98
	v_fmamk_f32 v81, v81, 0x3c800000, v207
	v_rsq_f32_e32 v81, v81
	s_nop 0
	v_mul_f32_e32 v98, v147, v81
	v_ashrrev_i32_e32 v81, 31, v80
	v_lshlrev_b64 v[100:101], 10, v[80:81]
	v_lshl_add_u64 v[100:101], s[54:55], 0, v[100:101]
	v_lshlrev_b32_e32 v81, 2, v146
	v_lshl_add_u64 v[108:109], s[46:47], 1, v[100:101]
	s_nop 1
	v_mov_b32_e32 v100, v236
	v_mov_b32_e32 v101, v237
	v_mov_b32_e32 v102, v238
	v_mov_b32_e32 v103, v239
	v_mov_b32_e32 v104, v232
	v_mov_b32_e32 v105, v233
	v_mov_b32_e32 v106, v234
	v_mov_b32_e32 v107, v235
	v_pk_mul_f32 v[110:111], v[92:93], v[98:99] op_sel_hi:[1,0]
	v_pk_mul_f32 v[112:113], v[94:95], v[98:99] op_sel_hi:[1,0]
	v_lshl_add_u64 v[108:109], v[108:109], 0, v[148:149]
	v_pk_mul_f32 v[106:107], v[106:107], v[112:113]
	v_pk_mul_f32 v[104:105], v[104:105], v[110:111]
	v_pk_mul_f32 v[110:111], v[96:97], v[98:99] op_sel_hi:[1,0]
	v_pk_mul_f32 v[112:113], v[90:91], v[98:99] op_sel_hi:[1,0]
	s_nop 0
	v_pk_mul_f32 v[112:113], v[102:103], v[112:113]
	v_pk_mul_f32 v[102:103], v[100:101], v[110:111]
	v_cvt_pk_bf16_f32 v100, v104, v105
	v_cvt_pk_bf16_f32 v101, v106, v107
	v_cvt_pk_bf16_f32 v102, v102, v103
	v_cvt_pk_bf16_f32 v103, v112, v113
	global_store_dwordx4 v[108:109], v[100:103], off
	s_nop 1
	v_mov_b32_e32 v100, v244
	v_mov_b32_e32 v101, v245
	v_mov_b32_e32 v102, v246
	v_mov_b32_e32 v103, v247
	v_mov_b32_e32 v104, v240
	v_mov_b32_e32 v105, v241
	v_mov_b32_e32 v106, v242
	v_mov_b32_e32 v107, v243
	v_pk_mul_f32 v[110:111], v[84:85], v[98:99] op_sel_hi:[1,0]
	v_pk_mul_f32 v[112:113], v[86:87], v[98:99] op_sel_hi:[1,0]
	v_pk_mul_f32 v[104:105], v[104:105], v[110:111]
	v_pk_mul_f32 v[110:111], v[88:89], v[98:99] op_sel_hi:[1,0]
	v_pk_mul_f32 v[98:99], v[82:83], v[98:99] op_sel_hi:[1,0]
	v_pk_mul_f32 v[106:107], v[106:107], v[112:113]
	v_pk_mul_f32 v[102:103], v[102:103], v[98:99]
	v_pk_mul_f32 v[100:101], v[100:101], v[110:111]
	v_cvt_pk_bf16_f32 v98, v104, v105
	v_cvt_pk_bf16_f32 v99, v106, v107
	v_cvt_pk_bf16_f32 v100, v100, v101
	v_cvt_pk_bf16_f32 v101, v102, v103
	global_store_dwordx4 v[108:109], v[98:101], off offset:64

.LBB0_655:
	s_andn2_b64 vcc, exec, s[52:53]
	s_cbranch_vccnz .LBB0_657
	v_mov_b32_e32 v84, v77
	v_mov_b32_e32 v85, v69
	v_mov_b32_e32 v82, v76
	v_mov_b32_e32 v83, v68
	v_pk_mul_f32 v[84:85], v[84:85], v[84:85]
	v_mov_b32_e32 v86, v79
	v_mov_b32_e32 v87, v71
	v_pk_fma_f32 v[82:83], v[82:83], v[82:83], v[84:85]
	v_mov_b32_e32 v84, v78
	v_mov_b32_e32 v85, v70
	v_pk_mul_f32 v[86:87], v[86:87], v[86:87]
	v_mov_b32_e32 v88, v75
	v_pk_fma_f32 v[84:85], v[84:85], v[84:85], v[86:87]
	v_mov_b32_e32 v86, v81
	v_mov_b32_e32 v87, v73
	v_pk_add_f32 v[82:83], v[82:83], v[84:85]
	v_mov_b32_e32 v84, v80
	v_mov_b32_e32 v85, v72
	v_pk_mul_f32 v[86:87], v[86:87], v[86:87]
	v_mov_b32_e32 v89, v67
	v_pk_fma_f32 v[84:85], v[84:85], v[84:85], v[86:87]
	v_mov_b32_e32 v86, v74
	v_mov_b32_e32 v87, v66
	v_pk_mul_f32 v[88:89], v[88:89], v[88:89]
	s_and_b64 s[52:53], s[10:11], exec
	v_pk_fma_f32 v[86:87], v[86:87], v[86:87], v[88:89]
	v_readlane_b32 s52, v253, 61
	v_pk_add_f32 v[84:85], v[84:85], v[86:87]
	v_readlane_b32 s53, v253, 62
	v_pk_add_f32 v[82:83], v[82:83], v[84:85]
	v_readlane_b32 s54, v253, 63
	v_add_f32_e32 v65, v82, v83
	v_and_b32_e32 v83, 64, v210
	v_xor_b32_e32 v82, 16, v210
	v_add_u32_e32 v83, 64, v83
	v_cmp_lt_i32_e32 vcc, v82, v83
	v_readlane_b32 s55, v254, 0
	s_cselect_b32 s53, s53, s55
	v_cndmask_b32_e32 v82, v210, v82, vcc
	v_lshlrev_b32_e32 v82, 2, v82
	ds_bpermute_b32 v82, v82, v65
	s_cselect_b32 s52, s52, s54
	s_cselect_b32 s55, s62, s64
	s_cselect_b32 s54, s61, s63
	v_lshlrev_b32_e32 v148, 1, v146
	s_waitcnt lgkmcnt(0)
	v_add_f32_e32 v65, v65, v82
	v_xor_b32_e32 v82, 32, v210
	v_cmp_lt_i32_e32 vcc, v82, v83
	s_nop 1
	v_cndmask_b32_e32 v82, v210, v82, vcc
	v_lshlrev_b32_e32 v82, 2, v82
	ds_bpermute_b32 v82, v82, v65
	s_waitcnt lgkmcnt(0)
	v_add_f32_e32 v65, v65, v82
	v_fmamk_f32 v65, v65, 0x3c800000, v207
	v_rsq_f32_e32 v65, v65
	s_nop 0
	v_mul_f32_e32 v82, v147, v65
	v_ashrrev_i32_e32 v65, 31, v64
	v_lshlrev_b64 v[84:85], 10, v[64:65]
	v_lshl_add_u64 v[84:85], s[54:55], 0, v[84:85]
	v_lshlrev_b32_e32 v65, 2, v146
	v_lshl_add_u64 v[92:93], s[46:47], 1, v[84:85]
	s_nop 1
	v_mov_b32_e32 v84, v236
	v_mov_b32_e32 v85, v237
	v_mov_b32_e32 v86, v238
	v_mov_b32_e32 v87, v239
	v_mov_b32_e32 v88, v232
	v_mov_b32_e32 v89, v233
	v_mov_b32_e32 v90, v234
	v_mov_b32_e32 v91, v235
	v_pk_mul_f32 v[94:95], v[76:77], v[82:83] op_sel_hi:[1,0]
	v_pk_mul_f32 v[96:97], v[78:79], v[82:83] op_sel_hi:[1,0]
	v_lshl_add_u64 v[92:93], v[92:93], 0, v[148:149]
	v_pk_mul_f32 v[90:91], v[90:91], v[96:97]
	v_pk_mul_f32 v[88:89], v[88:89], v[94:95]
	v_pk_mul_f32 v[94:95], v[80:81], v[82:83] op_sel_hi:[1,0]
	v_pk_mul_f32 v[96:97], v[74:75], v[82:83] op_sel_hi:[1,0]
	s_nop 0
	v_pk_mul_f32 v[96:97], v[86:87], v[96:97]
	v_pk_mul_f32 v[86:87], v[84:85], v[94:95]
	v_cvt_pk_bf16_f32 v84, v88, v89
	v_cvt_pk_bf16_f32 v85, v90, v91
	v_cvt_pk_bf16_f32 v86, v86, v87
	v_cvt_pk_bf16_f32 v87, v96, v97
	global_store_dwordx4 v[92:93], v[84:87], off
	s_nop 1
	v_mov_b32_e32 v84, v244
	v_mov_b32_e32 v85, v245
	v_mov_b32_e32 v86, v246
	v_mov_b32_e32 v87, v247
	v_mov_b32_e32 v88, v240
	v_mov_b32_e32 v89, v241
	v_mov_b32_e32 v90, v242
	v_mov_b32_e32 v91, v243
	v_pk_mul_f32 v[94:95], v[68:69], v[82:83] op_sel_hi:[1,0]
	v_pk_mul_f32 v[96:97], v[70:71], v[82:83] op_sel_hi:[1,0]
	v_pk_mul_f32 v[88:89], v[88:89], v[94:95]
	v_pk_mul_f32 v[94:95], v[72:73], v[82:83] op_sel_hi:[1,0]
	v_pk_mul_f32 v[82:83], v[66:67], v[82:83] op_sel_hi:[1,0]
	v_pk_mul_f32 v[90:91], v[90:91], v[96:97]
	v_pk_mul_f32 v[86:87], v[86:87], v[82:83]
	v_pk_mul_f32 v[84:85], v[84:85], v[94:95]
	v_cvt_pk_bf16_f32 v82, v88, v89
	v_cvt_pk_bf16_f32 v83, v90, v91
	v_cvt_pk_bf16_f32 v84, v84, v85
	v_cvt_pk_bf16_f32 v85, v86, v87
	global_store_dwordx4 v[92:93], v[82:85], off offset:64

.LBB0_674:
	s_andn2_b64 vcc, exec, s[52:53]
	s_cbranch_vccnz .LBB0_676
	v_mov_b32_e32 v68, v61
	v_mov_b32_e32 v69, v53
	v_mov_b32_e32 v66, v60
	v_mov_b32_e32 v67, v52
	v_pk_mul_f32 v[68:69], v[68:69], v[68:69]
	v_mov_b32_e32 v70, v63
	v_mov_b32_e32 v71, v55
	v_pk_fma_f32 v[66:67], v[66:67], v[66:67], v[68:69]
	v_mov_b32_e32 v68, v62
	v_mov_b32_e32 v69, v54
	v_pk_mul_f32 v[70:71], v[70:71], v[70:71]
	v_mov_b32_e32 v72, v59
	v_pk_fma_f32 v[68:69], v[68:69], v[68:69], v[70:71]
	v_mov_b32_e32 v70, v57
	v_mov_b32_e32 v71, v49
	v_pk_add_f32 v[66:67], v[66:67], v[68:69]
	v_mov_b32_e32 v68, v56
	v_mov_b32_e32 v69, v48
	v_pk_mul_f32 v[70:71], v[70:71], v[70:71]
	v_mov_b32_e32 v73, v51
	v_pk_fma_f32 v[68:69], v[68:69], v[68:69], v[70:71]
	v_mov_b32_e32 v70, v58
	v_mov_b32_e32 v71, v50
	v_pk_mul_f32 v[72:73], v[72:73], v[72:73]
	s_and_b64 s[52:53], s[10:11], exec
	v_pk_fma_f32 v[70:71], v[70:71], v[70:71], v[72:73]
	v_readlane_b32 s52, v253, 61
	v_pk_add_f32 v[68:69], v[68:69], v[70:71]
	v_readlane_b32 s53, v253, 62
	v_pk_add_f32 v[66:67], v[66:67], v[68:69]
	v_readlane_b32 s54, v253, 63
	v_add_f32_e32 v65, v66, v67
	v_and_b32_e32 v67, 64, v210
	v_xor_b32_e32 v66, 16, v210
	v_add_u32_e32 v67, 64, v67
	v_cmp_lt_i32_e32 vcc, v66, v67
	v_readlane_b32 s55, v254, 0
	s_cselect_b32 s53, s53, s55
	v_cndmask_b32_e32 v66, v210, v66, vcc
	v_lshlrev_b32_e32 v66, 2, v66
	ds_bpermute_b32 v66, v66, v65
	s_cselect_b32 s52, s52, s54
	s_cselect_b32 s55, s62, s64
	s_cselect_b32 s54, s61, s63
	v_lshlrev_b32_e32 v148, 1, v146
	s_waitcnt lgkmcnt(0)
	v_add_f32_e32 v65, v65, v66
	v_xor_b32_e32 v66, 32, v210
	v_cmp_lt_i32_e32 vcc, v66, v67
	s_nop 1
	v_cndmask_b32_e32 v66, v210, v66, vcc
	v_lshlrev_b32_e32 v66, 2, v66
	ds_bpermute_b32 v66, v66, v65
	s_waitcnt lgkmcnt(0)
	v_add_f32_e32 v65, v65, v66
	v_fmamk_f32 v65, v65, 0x3c800000, v207
	v_rsq_f32_e32 v65, v65
	s_nop 0
	v_mul_f32_e32 v66, v147, v65
	v_ashrrev_i32_e32 v65, 31, v64
	v_lshlrev_b64 v[68:69], 10, v[64:65]
	v_lshl_add_u64 v[68:69], s[54:55], 0, v[68:69]
	v_lshlrev_b32_e32 v65, 2, v146
	v_lshl_add_u64 v[76:77], s[46:47], 1, v[68:69]
	s_nop 1
	v_mov_b32_e32 v68, v236
	v_mov_b32_e32 v69, v237
	v_mov_b32_e32 v70, v238
	v_mov_b32_e32 v71, v239
	v_mov_b32_e32 v72, v232
	v_mov_b32_e32 v73, v233
	v_mov_b32_e32 v74, v234
	v_mov_b32_e32 v75, v235
	v_pk_mul_f32 v[78:79], v[60:61], v[66:67] op_sel_hi:[1,0]
	v_pk_mul_f32 v[80:81], v[62:63], v[66:67] op_sel_hi:[1,0]
	v_lshl_add_u64 v[76:77], v[76:77], 0, v[148:149]
	v_pk_mul_f32 v[74:75], v[74:75], v[80:81]
	v_pk_mul_f32 v[72:73], v[72:73], v[78:79]
	v_pk_mul_f32 v[78:79], v[56:57], v[66:67] op_sel_hi:[1,0]
	v_pk_mul_f32 v[80:81], v[58:59], v[66:67] op_sel_hi:[1,0]
	s_nop 0
	v_pk_mul_f32 v[80:81], v[70:71], v[80:81]
	v_pk_mul_f32 v[70:71], v[68:69], v[78:79]
	v_cvt_pk_bf16_f32 v68, v72, v73
	v_cvt_pk_bf16_f32 v69, v74, v75
	v_cvt_pk_bf16_f32 v70, v70, v71
	v_cvt_pk_bf16_f32 v71, v80, v81
	global_store_dwordx4 v[76:77], v[68:71], off
	s_nop 1
	v_mov_b32_e32 v68, v244
	v_mov_b32_e32 v69, v245
	v_mov_b32_e32 v70, v246
	v_mov_b32_e32 v71, v247
	v_mov_b32_e32 v72, v240
	v_mov_b32_e32 v73, v241
	v_mov_b32_e32 v74, v242
	v_mov_b32_e32 v75, v243
	v_pk_mul_f32 v[78:79], v[52:53], v[66:67] op_sel_hi:[1,0]
	v_pk_mul_f32 v[80:81], v[54:55], v[66:67] op_sel_hi:[1,0]
	v_pk_mul_f32 v[72:73], v[72:73], v[78:79]
	v_pk_mul_f32 v[78:79], v[48:49], v[66:67] op_sel_hi:[1,0]
	v_pk_mul_f32 v[66:67], v[50:51], v[66:67] op_sel_hi:[1,0]
	v_pk_mul_f32 v[74:75], v[74:75], v[80:81]
	v_pk_mul_f32 v[70:71], v[70:71], v[66:67]
	v_pk_mul_f32 v[68:69], v[68:69], v[78:79]
	v_cvt_pk_bf16_f32 v66, v72, v73
	v_cvt_pk_bf16_f32 v67, v74, v75
	v_cvt_pk_bf16_f32 v68, v68, v69
	v_cvt_pk_bf16_f32 v69, v70, v71
	global_store_dwordx4 v[76:77], v[66:69], off offset:64

.LBB0_693:
	s_andn2_b64 vcc, exec, s[52:53]
	s_cbranch_vccnz .LBB0_695
	v_mov_b32_e32 v52, v45
	v_mov_b32_e32 v53, v37
	v_mov_b32_e32 v50, v44
	v_mov_b32_e32 v51, v36
	v_pk_mul_f32 v[52:53], v[52:53], v[52:53]
	v_mov_b32_e32 v54, v47
	v_mov_b32_e32 v55, v39
	v_pk_fma_f32 v[50:51], v[50:51], v[50:51], v[52:53]
	v_mov_b32_e32 v52, v46
	v_mov_b32_e32 v53, v38
	v_pk_mul_f32 v[54:55], v[54:55], v[54:55]
	v_mov_b32_e32 v56, v43
	v_pk_fma_f32 v[52:53], v[52:53], v[52:53], v[54:55]
	v_mov_b32_e32 v54, v49
	v_mov_b32_e32 v55, v41
	v_pk_add_f32 v[50:51], v[50:51], v[52:53]
	v_mov_b32_e32 v52, v48
	v_mov_b32_e32 v53, v40
	v_pk_mul_f32 v[54:55], v[54:55], v[54:55]
	v_mov_b32_e32 v57, v35
	v_pk_fma_f32 v[52:53], v[52:53], v[52:53], v[54:55]
	v_mov_b32_e32 v54, v42
	v_mov_b32_e32 v55, v34
	v_pk_mul_f32 v[56:57], v[56:57], v[56:57]
	s_and_b64 s[52:53], s[10:11], exec
	v_pk_fma_f32 v[54:55], v[54:55], v[54:55], v[56:57]
	v_readlane_b32 s52, v253, 61
	v_pk_add_f32 v[52:53], v[52:53], v[54:55]
	v_readlane_b32 s53, v253, 62
	v_pk_add_f32 v[50:51], v[50:51], v[52:53]
	v_readlane_b32 s54, v253, 63
	v_add_f32_e32 v33, v50, v51
	v_and_b32_e32 v51, 64, v210
	v_xor_b32_e32 v50, 16, v210
	v_add_u32_e32 v51, 64, v51
	v_cmp_lt_i32_e32 vcc, v50, v51
	v_readlane_b32 s55, v254, 0
	s_cselect_b32 s53, s53, s55
	v_cndmask_b32_e32 v50, v210, v50, vcc
	v_lshlrev_b32_e32 v50, 2, v50
	ds_bpermute_b32 v50, v50, v33
	s_cselect_b32 s52, s52, s54
	s_cselect_b32 s55, s62, s64
	s_cselect_b32 s54, s61, s63
	v_lshlrev_b32_e32 v148, 1, v146
	s_waitcnt lgkmcnt(0)
	v_add_f32_e32 v33, v33, v50
	v_xor_b32_e32 v50, 32, v210
	v_cmp_lt_i32_e32 vcc, v50, v51
	s_nop 1
	v_cndmask_b32_e32 v50, v210, v50, vcc
	v_lshlrev_b32_e32 v50, 2, v50
	ds_bpermute_b32 v50, v50, v33
	s_waitcnt lgkmcnt(0)
	v_add_f32_e32 v33, v33, v50
	v_fmamk_f32 v33, v33, 0x3c800000, v207
	v_rsq_f32_e32 v33, v33
	s_nop 0
	v_mul_f32_e32 v50, v147, v33
	v_ashrrev_i32_e32 v33, 31, v32
	v_lshlrev_b64 v[52:53], 10, v[32:33]
	v_lshl_add_u64 v[52:53], s[54:55], 0, v[52:53]
	v_lshlrev_b32_e32 v33, 2, v146
	v_lshl_add_u64 v[60:61], s[46:47], 1, v[52:53]
	s_nop 1
	v_mov_b32_e32 v52, v236
	v_mov_b32_e32 v53, v237
	v_mov_b32_e32 v54, v238
	v_mov_b32_e32 v55, v239
	v_mov_b32_e32 v56, v232
	v_mov_b32_e32 v57, v233
	v_mov_b32_e32 v58, v234
	v_mov_b32_e32 v59, v235
	v_pk_mul_f32 v[62:63], v[44:45], v[50:51] op_sel_hi:[1,0]
	v_pk_mul_f32 v[64:65], v[46:47], v[50:51] op_sel_hi:[1,0]
	v_lshl_add_u64 v[60:61], v[60:61], 0, v[148:149]
	v_pk_mul_f32 v[58:59], v[58:59], v[64:65]
	v_pk_mul_f32 v[56:57], v[56:57], v[62:63]
	v_pk_mul_f32 v[62:63], v[48:49], v[50:51] op_sel_hi:[1,0]
	v_pk_mul_f32 v[64:65], v[42:43], v[50:51] op_sel_hi:[1,0]
	s_nop 0
	v_pk_mul_f32 v[64:65], v[54:55], v[64:65]
	v_pk_mul_f32 v[54:55], v[52:53], v[62:63]
	v_cvt_pk_bf16_f32 v52, v56, v57
	v_cvt_pk_bf16_f32 v53, v58, v59
	v_cvt_pk_bf16_f32 v54, v54, v55
	v_cvt_pk_bf16_f32 v55, v64, v65
	global_store_dwordx4 v[60:61], v[52:55], off
	s_nop 1
	v_mov_b32_e32 v52, v244
	v_mov_b32_e32 v53, v245
	v_mov_b32_e32 v54, v246
	v_mov_b32_e32 v55, v247
	v_mov_b32_e32 v56, v240
	v_mov_b32_e32 v57, v241
	v_mov_b32_e32 v58, v242
	v_mov_b32_e32 v59, v243
	v_pk_mul_f32 v[62:63], v[36:37], v[50:51] op_sel_hi:[1,0]
	v_pk_mul_f32 v[64:65], v[38:39], v[50:51] op_sel_hi:[1,0]
	v_pk_mul_f32 v[56:57], v[56:57], v[62:63]
	v_pk_mul_f32 v[62:63], v[40:41], v[50:51] op_sel_hi:[1,0]
	v_pk_mul_f32 v[50:51], v[34:35], v[50:51] op_sel_hi:[1,0]
	v_pk_mul_f32 v[58:59], v[58:59], v[64:65]
	v_pk_mul_f32 v[54:55], v[54:55], v[50:51]
	v_pk_mul_f32 v[52:53], v[52:53], v[62:63]
	v_cvt_pk_bf16_f32 v50, v56, v57
	v_cvt_pk_bf16_f32 v51, v58, v59
	v_cvt_pk_bf16_f32 v52, v52, v53
	v_cvt_pk_bf16_f32 v53, v54, v55
	global_store_dwordx4 v[60:61], v[50:53], off offset:64

.LBB0_712:
	s_andn2_b64 vcc, exec, s[52:53]
	s_cbranch_vccnz .LBB0_714
	v_mov_b32_e32 v36, v29
	v_mov_b32_e32 v37, v21
	v_mov_b32_e32 v34, v28
	v_mov_b32_e32 v35, v20
	v_pk_mul_f32 v[36:37], v[36:37], v[36:37]
	v_mov_b32_e32 v38, v31
	v_mov_b32_e32 v39, v23
	v_pk_fma_f32 v[34:35], v[34:35], v[34:35], v[36:37]
	v_mov_b32_e32 v36, v30
	v_mov_b32_e32 v37, v22
	v_pk_mul_f32 v[38:39], v[38:39], v[38:39]
	v_mov_b32_e32 v40, v27
	v_pk_fma_f32 v[36:37], v[36:37], v[36:37], v[38:39]
	v_mov_b32_e32 v38, v33
	v_mov_b32_e32 v39, v25
	v_pk_add_f32 v[34:35], v[34:35], v[36:37]
	v_mov_b32_e32 v36, v32
	v_mov_b32_e32 v37, v24
	v_pk_mul_f32 v[38:39], v[38:39], v[38:39]
	v_mov_b32_e32 v41, v19
	v_pk_fma_f32 v[36:37], v[36:37], v[36:37], v[38:39]
	v_mov_b32_e32 v38, v26
	v_mov_b32_e32 v39, v18
	v_pk_mul_f32 v[40:41], v[40:41], v[40:41]
	s_and_b64 s[52:53], s[10:11], exec
	v_pk_fma_f32 v[38:39], v[38:39], v[38:39], v[40:41]
	v_readlane_b32 s52, v253, 61
	v_pk_add_f32 v[36:37], v[36:37], v[38:39]
	v_readlane_b32 s53, v253, 62
	v_pk_add_f32 v[34:35], v[34:35], v[36:37]
	v_readlane_b32 s54, v253, 63
	v_add_f32_e32 v17, v34, v35
	v_and_b32_e32 v35, 64, v210
	v_xor_b32_e32 v34, 16, v210
	v_add_u32_e32 v35, 64, v35
	v_cmp_lt_i32_e32 vcc, v34, v35
	v_readlane_b32 s55, v254, 0
	s_cselect_b32 s53, s53, s55
	v_cndmask_b32_e32 v34, v210, v34, vcc
	v_lshlrev_b32_e32 v34, 2, v34
	ds_bpermute_b32 v34, v34, v17
	s_cselect_b32 s52, s52, s54
	s_cselect_b32 s55, s62, s64
	s_cselect_b32 s54, s61, s63
	v_lshlrev_b32_e32 v148, 1, v146
	s_waitcnt lgkmcnt(0)
	v_add_f32_e32 v17, v17, v34
	v_xor_b32_e32 v34, 32, v210
	v_cmp_lt_i32_e32 vcc, v34, v35
	s_nop 1
	v_cndmask_b32_e32 v34, v210, v34, vcc
	v_lshlrev_b32_e32 v34, 2, v34
	ds_bpermute_b32 v34, v34, v17
	s_waitcnt lgkmcnt(0)
	v_add_f32_e32 v17, v17, v34
	v_fmamk_f32 v17, v17, 0x3c800000, v207
	v_rsq_f32_e32 v17, v17
	s_nop 0
	v_mul_f32_e32 v34, v147, v17
	v_ashrrev_i32_e32 v17, 31, v16
	v_lshlrev_b64 v[36:37], 10, v[16:17]
	v_lshl_add_u64 v[36:37], s[54:55], 0, v[36:37]
	v_lshlrev_b32_e32 v17, 2, v146
	v_lshl_add_u64 v[44:45], s[46:47], 1, v[36:37]
	s_nop 1
	v_mov_b32_e32 v36, v236
	v_mov_b32_e32 v37, v237
	v_mov_b32_e32 v38, v238
	v_mov_b32_e32 v39, v239
	v_mov_b32_e32 v40, v232
	v_mov_b32_e32 v41, v233
	v_mov_b32_e32 v42, v234
	v_mov_b32_e32 v43, v235
	v_pk_mul_f32 v[46:47], v[28:29], v[34:35] op_sel_hi:[1,0]
	v_pk_mul_f32 v[48:49], v[30:31], v[34:35] op_sel_hi:[1,0]
	v_lshl_add_u64 v[44:45], v[44:45], 0, v[148:149]
	v_pk_mul_f32 v[42:43], v[42:43], v[48:49]
	v_pk_mul_f32 v[40:41], v[40:41], v[46:47]
	v_pk_mul_f32 v[46:47], v[32:33], v[34:35] op_sel_hi:[1,0]
	v_pk_mul_f32 v[48:49], v[26:27], v[34:35] op_sel_hi:[1,0]
	s_nop 0
	v_pk_mul_f32 v[48:49], v[38:39], v[48:49]
	v_pk_mul_f32 v[38:39], v[36:37], v[46:47]
	v_cvt_pk_bf16_f32 v36, v40, v41
	v_cvt_pk_bf16_f32 v37, v42, v43
	v_cvt_pk_bf16_f32 v38, v38, v39
	v_cvt_pk_bf16_f32 v39, v48, v49
	global_store_dwordx4 v[44:45], v[36:39], off
	s_nop 1
	v_mov_b32_e32 v36, v244
	v_mov_b32_e32 v37, v245
	v_mov_b32_e32 v38, v246
	v_mov_b32_e32 v39, v247
	v_mov_b32_e32 v40, v240
	v_mov_b32_e32 v41, v241
	v_mov_b32_e32 v42, v242
	v_mov_b32_e32 v43, v243
	v_pk_mul_f32 v[46:47], v[20:21], v[34:35] op_sel_hi:[1,0]
	v_pk_mul_f32 v[48:49], v[22:23], v[34:35] op_sel_hi:[1,0]
	v_pk_mul_f32 v[40:41], v[40:41], v[46:47]
	v_pk_mul_f32 v[46:47], v[24:25], v[34:35] op_sel_hi:[1,0]
	v_pk_mul_f32 v[34:35], v[18:19], v[34:35] op_sel_hi:[1,0]
	v_pk_mul_f32 v[42:43], v[42:43], v[48:49]
	v_pk_mul_f32 v[38:39], v[38:39], v[34:35]
	v_pk_mul_f32 v[36:37], v[36:37], v[46:47]
	v_cvt_pk_bf16_f32 v34, v40, v41
	v_cvt_pk_bf16_f32 v35, v42, v43
	v_cvt_pk_bf16_f32 v36, v36, v37
	v_cvt_pk_bf16_f32 v37, v38, v39
	global_store_dwordx4 v[44:45], v[34:37], off offset:64

.LBB0_733:
	s_andn2_b64 vcc, exec, s[14:15]
	s_cbranch_vccnz .LBB0_735
	v_mov_b32_e32 v20, v13
	v_mov_b32_e32 v21, v5
	v_mov_b32_e32 v18, v12
	v_mov_b32_e32 v19, v4
	v_pk_mul_f32 v[20:21], v[20:21], v[20:21]
	v_mov_b32_e32 v22, v15
	v_mov_b32_e32 v23, v7
	v_pk_fma_f32 v[18:19], v[18:19], v[18:19], v[20:21]
	v_mov_b32_e32 v20, v14
	v_mov_b32_e32 v21, v6
	v_pk_mul_f32 v[22:23], v[22:23], v[22:23]
	v_mov_b32_e32 v24, v11
	v_pk_fma_f32 v[20:21], v[20:21], v[20:21], v[22:23]
	v_mov_b32_e32 v22, v17
	v_mov_b32_e32 v23, v9
	v_pk_add_f32 v[18:19], v[18:19], v[20:21]
	v_mov_b32_e32 v20, v16
	v_mov_b32_e32 v21, v8
	v_pk_mul_f32 v[22:23], v[22:23], v[22:23]
	v_mov_b32_e32 v25, v3
	v_pk_fma_f32 v[20:21], v[20:21], v[20:21], v[22:23]
	v_mov_b32_e32 v22, v10
	v_mov_b32_e32 v23, v2
	v_pk_mul_f32 v[24:25], v[24:25], v[24:25]
	s_and_b64 s[10:11], s[10:11], exec
	v_pk_fma_f32 v[22:23], v[22:23], v[22:23], v[24:25]
	v_readlane_b32 s52, v253, 61
	v_pk_add_f32 v[20:21], v[20:21], v[22:23]
	v_readlane_b32 s53, v253, 62
	v_pk_add_f32 v[18:19], v[18:19], v[20:21]
	v_readlane_b32 s54, v253, 63
	v_add_f32_e32 v1, v18, v19
	v_and_b32_e32 v19, 64, v210
	v_xor_b32_e32 v18, 16, v210
	v_add_u32_e32 v19, 64, v19
	v_cmp_lt_i32_e32 vcc, v18, v19
	v_readlane_b32 s55, v254, 0
	s_cselect_b32 s15, s62, s64
	v_cndmask_b32_e32 v18, v210, v18, vcc
	v_lshlrev_b32_e32 v18, 2, v18
	ds_bpermute_b32 v18, v18, v1
	s_cselect_b32 s14, s61, s63
	s_cselect_b32 s11, s53, s55
	s_cselect_b32 s10, s52, s54
	v_lshlrev_b32_e32 v148, 1, v146
	s_waitcnt lgkmcnt(0)
	v_add_f32_e32 v1, v1, v18
	v_xor_b32_e32 v18, 32, v210
	v_cmp_lt_i32_e32 vcc, v18, v19
	s_nop 1
	v_cndmask_b32_e32 v18, v210, v18, vcc
	v_lshlrev_b32_e32 v18, 2, v18
	ds_bpermute_b32 v18, v18, v1
	s_waitcnt lgkmcnt(0)
	v_add_f32_e32 v1, v1, v18
	v_fmamk_f32 v1, v1, 0x3c800000, v207
	v_rsq_f32_e32 v1, v1
	s_nop 0
	v_mul_f32_e32 v18, v147, v1
	v_ashrrev_i32_e32 v1, 31, v0
	v_lshlrev_b64 v[20:21], 10, v[0:1]
	v_lshl_add_u64 v[20:21], s[14:15], 0, v[20:21]
	v_lshlrev_b32_e32 v1, 2, v146
	v_lshl_add_u64 v[28:29], s[46:47], 1, v[20:21]
	s_nop 1
	v_mov_b32_e32 v20, v236
	v_mov_b32_e32 v21, v237
	v_mov_b32_e32 v22, v238
	v_mov_b32_e32 v23, v239
	v_mov_b32_e32 v24, v232
	v_mov_b32_e32 v25, v233
	v_mov_b32_e32 v26, v234
	v_mov_b32_e32 v27, v235
	v_pk_mul_f32 v[30:31], v[12:13], v[18:19] op_sel_hi:[1,0]
	v_pk_mul_f32 v[32:33], v[14:15], v[18:19] op_sel_hi:[1,0]
	v_lshl_add_u64 v[28:29], v[28:29], 0, v[148:149]
	v_pk_mul_f32 v[26:27], v[26:27], v[32:33]
	v_pk_mul_f32 v[24:25], v[24:25], v[30:31]
	v_pk_mul_f32 v[30:31], v[16:17], v[18:19] op_sel_hi:[1,0]
	v_pk_mul_f32 v[32:33], v[10:11], v[18:19] op_sel_hi:[1,0]
	s_nop 0
	v_pk_mul_f32 v[32:33], v[22:23], v[32:33]
	v_pk_mul_f32 v[22:23], v[20:21], v[30:31]
	v_cvt_pk_bf16_f32 v20, v24, v25
	v_cvt_pk_bf16_f32 v21, v26, v27
	v_cvt_pk_bf16_f32 v22, v22, v23
	v_cvt_pk_bf16_f32 v23, v32, v33
	global_store_dwordx4 v[28:29], v[20:23], off
	s_nop 1
	v_mov_b32_e32 v20, v244
	v_mov_b32_e32 v21, v245
	v_mov_b32_e32 v22, v246
	v_mov_b32_e32 v23, v247
	v_mov_b32_e32 v24, v240
	v_mov_b32_e32 v25, v241
	v_mov_b32_e32 v26, v242
	v_mov_b32_e32 v27, v243
	v_pk_mul_f32 v[30:31], v[4:5], v[18:19] op_sel_hi:[1,0]
	v_pk_mul_f32 v[32:33], v[6:7], v[18:19] op_sel_hi:[1,0]
	v_pk_mul_f32 v[24:25], v[24:25], v[30:31]
	v_pk_mul_f32 v[30:31], v[8:9], v[18:19] op_sel_hi:[1,0]
	v_pk_mul_f32 v[18:19], v[2:3], v[18:19] op_sel_hi:[1,0]
	v_pk_mul_f32 v[26:27], v[26:27], v[32:33]
	v_pk_mul_f32 v[22:23], v[22:23], v[18:19]
	v_pk_mul_f32 v[20:21], v[20:21], v[30:31]
	v_cvt_pk_bf16_f32 v18, v24, v25
	v_cvt_pk_bf16_f32 v19, v26, v27
	v_cvt_pk_bf16_f32 v20, v20, v21
	v_cvt_pk_bf16_f32 v21, v22, v23
	global_store_dwordx4 v[28:29], v[18:21], off offset:64

.LBB0_1441:
	s_lshl_b32 s11, s43, 8
	s_add_i32 s11, s11, s37
	v_and_b32_e32 v150, 15, v206
	v_add_u32_e32 v150, s11, v150
	v_bfe_u32 v151, v206, 4, 2
	s_lshl_b32 s11, s42, 8
	s_or_b32 s11, s11, s38
	v_lshl_or_b32 v152, v151, 3, s11
	s_mov_b32 s49, s53
	v_lshlrev_b32_e32 v138, 11, v150
	v_lshl_add_u32 v138, v152, 1, v138
	v_add_u32_e32 v139, 0x8000, v138
	v_add_u32_e32 v140, 0x10000, v138
	v_add_u32_e32 v141, 0x18000, v138
	v_add_u32_e32 v142, 0x40000, v138
	v_add_u32_e32 v146, 0x48000, v138
	v_add_u32_e32 v147, 0x50000, v138
	v_add_u32_e32 v219, 0x58000, v138
	s_lshl_b32 s18, s42, 4
	s_lshl_b32 s19, s36, 2
	s_add_i32 s18, s18, s19
	v_lshlrev_b32_e32 v150, 6, v150
	v_add_u32_e32 v150, s18, v150
	global_load_dwordx4 v[160:163], v138, s[90:91]
	global_load_dwordx4 v[164:167], v138, s[90:91] offset:256
	global_load_dwordx4 v[168:171], v139, s[90:91]
	global_load_dwordx4 v[172:175], v139, s[90:91] offset:256
	global_load_dwordx4 v[176:179], v140, s[90:91]
	global_load_dwordx4 v[180:183], v140, s[90:91] offset:256
	global_load_dwordx4 v[184:187], v141, s[90:91]
	global_load_dwordx4 v[188:191], v141, s[90:91] offset:256
	global_load_dwordx4 v[192:195], v142, s[90:91]
	global_load_dwordx4 v[196:199], v142, s[90:91] offset:256
	global_load_dwordx4 v[200:203], v146, s[90:91]
	global_load_dwordx4 v[212:215], v146, s[90:91] offset:256
	global_load_dwordx4 v[220:223], v147, s[90:91]
	global_load_dwordx4 v[224:227], v147, s[90:91] offset:256
	global_load_dwordx4 v[228:231], v219, s[90:91]
	global_load_dwordx4 v[232:235], v219, s[90:91] offset:256
	s_waitcnt vmcnt(15)
	v_lshlrev_b32_e32 v152, 16, v160
	v_and_b32_e32 v153, 0xffff0000, v160
	v_pk_add_f32 v[124:125], v[124:125], v[152:153]
	v_lshlrev_b32_e32 v154, 16, v161
	v_and_b32_e32 v155, 0xffff0000, v161
	v_pk_add_f32 v[126:127], v[126:127], v[154:155]
	v_lshlrev_b32_e32 v156, 16, v162
	v_and_b32_e32 v157, 0xffff0000, v162
	v_pk_add_f32 v[120:121], v[120:121], v[156:157]
	v_lshlrev_b32_e32 v158, 16, v163
	v_and_b32_e32 v159, 0xffff0000, v163
	v_pk_add_f32 v[122:123], v[122:123], v[158:159]
	v_cvt_pk_bf16_f32 v236, v124, v125
	v_cvt_pk_bf16_f32 v237, v126, v127
	v_cvt_pk_bf16_f32 v238, v120, v121
	v_cvt_pk_bf16_f32 v239, v122, v123
	global_store_dwordx4 v138, v[236:239], s[2:3]
	v_mul_f32_e32 v152, v125, v125
	v_mul_f32_e32 v153, v127, v127
	v_fmac_f32_e32 v152, v124, v124
	v_fmac_f32_e32 v153, v126, v126
	v_add_f32_e32 v152, v152, v153
	v_mul_f32_e32 v153, v121, v121
	v_mul_f32_e32 v154, v123, v123
	v_fmac_f32_e32 v153, v120, v120
	v_fmac_f32_e32 v154, v122, v122
	v_add_f32_e32 v153, v153, v154
	v_add_f32_e32 v244, v152, v153
	s_waitcnt vmcnt(15)
	v_lshlrev_b32_e32 v152, 16, v164
	v_and_b32_e32 v153, 0xffff0000, v164
	v_pk_add_f32 v[116:117], v[116:117], v[152:153]
	v_lshlrev_b32_e32 v154, 16, v165
	v_and_b32_e32 v155, 0xffff0000, v165
	v_pk_add_f32 v[118:119], v[118:119], v[154:155]
	v_lshlrev_b32_e32 v156, 16, v166
	v_and_b32_e32 v157, 0xffff0000, v166
	v_pk_add_f32 v[112:113], v[112:113], v[156:157]
	v_lshlrev_b32_e32 v158, 16, v167
	v_and_b32_e32 v159, 0xffff0000, v167
	v_pk_add_f32 v[114:115], v[114:115], v[158:159]
	v_cvt_pk_bf16_f32 v240, v116, v117
	v_cvt_pk_bf16_f32 v241, v118, v119
	v_cvt_pk_bf16_f32 v242, v112, v113
	v_cvt_pk_bf16_f32 v243, v114, v115
	global_store_dwordx4 v138, v[240:243], s[2:3] offset:256
	v_mul_f32_e32 v152, v117, v117
	v_mul_f32_e32 v153, v119, v119
	v_fmac_f32_e32 v152, v116, v116
	v_fmac_f32_e32 v153, v118, v118
	v_add_f32_e32 v152, v152, v153
	v_mul_f32_e32 v153, v113, v113
	v_mul_f32_e32 v154, v115, v115
	v_fmac_f32_e32 v153, v112, v112
	v_fmac_f32_e32 v154, v114, v114
	v_add_f32_e32 v153, v153, v154
	v_add_f32_e32 v152, v152, v153
	v_add_f32_e32 v244, v244, v152
	s_waitcnt vmcnt(15)
	v_lshlrev_b32_e32 v152, 16, v168
	v_and_b32_e32 v153, 0xffff0000, v168
	v_pk_add_f32 v[108:109], v[108:109], v[152:153]
	v_lshlrev_b32_e32 v154, 16, v169
	v_and_b32_e32 v155, 0xffff0000, v169
	v_pk_add_f32 v[110:111], v[110:111], v[154:155]
	v_lshlrev_b32_e32 v156, 16, v170
	v_and_b32_e32 v157, 0xffff0000, v170
	v_pk_add_f32 v[104:105], v[104:105], v[156:157]
	v_lshlrev_b32_e32 v158, 16, v171
	v_and_b32_e32 v159, 0xffff0000, v171
	v_pk_add_f32 v[106:107], v[106:107], v[158:159]
	v_cvt_pk_bf16_f32 v236, v108, v109
	v_cvt_pk_bf16_f32 v237, v110, v111
	v_cvt_pk_bf16_f32 v238, v104, v105
	v_cvt_pk_bf16_f32 v239, v106, v107
	global_store_dwordx4 v139, v[236:239], s[2:3]
	v_mul_f32_e32 v152, v109, v109
	v_mul_f32_e32 v153, v111, v111
	v_fmac_f32_e32 v152, v108, v108
	v_fmac_f32_e32 v153, v110, v110
	v_add_f32_e32 v152, v152, v153
	v_mul_f32_e32 v153, v105, v105
	v_mul_f32_e32 v154, v107, v107
	v_fmac_f32_e32 v153, v104, v104
	v_fmac_f32_e32 v154, v106, v106
	v_add_f32_e32 v153, v153, v154
	v_add_f32_e32 v245, v152, v153
	s_waitcnt vmcnt(15)
	v_lshlrev_b32_e32 v152, 16, v172
	v_and_b32_e32 v153, 0xffff0000, v172
	v_pk_add_f32 v[100:101], v[100:101], v[152:153]
	v_lshlrev_b32_e32 v154, 16, v173
	v_and_b32_e32 v155, 0xffff0000, v173
	v_pk_add_f32 v[102:103], v[102:103], v[154:155]
	v_lshlrev_b32_e32 v156, 16, v174
	v_and_b32_e32 v157, 0xffff0000, v174
	v_pk_add_f32 v[96:97], v[96:97], v[156:157]
	v_lshlrev_b32_e32 v158, 16, v175
	v_and_b32_e32 v159, 0xffff0000, v175
	v_pk_add_f32 v[98:99], v[98:99], v[158:159]
	v_cvt_pk_bf16_f32 v240, v100, v101
	v_cvt_pk_bf16_f32 v241, v102, v103
	v_cvt_pk_bf16_f32 v242, v96, v97
	v_cvt_pk_bf16_f32 v243, v98, v99
	global_store_dwordx4 v139, v[240:243], s[2:3] offset:256
	v_mul_f32_e32 v152, v101, v101
	v_mul_f32_e32 v153, v103, v103
	v_fmac_f32_e32 v152, v100, v100
	v_fmac_f32_e32 v153, v102, v102
	v_add_f32_e32 v152, v152, v153
	v_mul_f32_e32 v153, v97, v97
	v_mul_f32_e32 v154, v99, v99
	v_fmac_f32_e32 v153, v96, v96
	v_fmac_f32_e32 v154, v98, v98
	v_add_f32_e32 v153, v153, v154
	v_add_f32_e32 v152, v152, v153
	v_add_f32_e32 v245, v245, v152
	s_waitcnt vmcnt(15)
	v_lshlrev_b32_e32 v152, 16, v176
	v_and_b32_e32 v153, 0xffff0000, v176
	v_pk_add_f32 v[92:93], v[92:93], v[152:153]
	v_lshlrev_b32_e32 v154, 16, v177
	v_and_b32_e32 v155, 0xffff0000, v177
	v_pk_add_f32 v[94:95], v[94:95], v[154:155]
	v_lshlrev_b32_e32 v156, 16, v178
	v_and_b32_e32 v157, 0xffff0000, v178
	v_pk_add_f32 v[88:89], v[88:89], v[156:157]
	v_lshlrev_b32_e32 v158, 16, v179
	v_and_b32_e32 v159, 0xffff0000, v179
	v_pk_add_f32 v[90:91], v[90:91], v[158:159]
	v_cvt_pk_bf16_f32 v236, v92, v93
	v_cvt_pk_bf16_f32 v237, v94, v95
	v_cvt_pk_bf16_f32 v238, v88, v89
	v_cvt_pk_bf16_f32 v239, v90, v91
	global_store_dwordx4 v140, v[236:239], s[2:3]
	v_mul_f32_e32 v152, v93, v93
	v_mul_f32_e32 v153, v95, v95
	v_fmac_f32_e32 v152, v92, v92
	v_fmac_f32_e32 v153, v94, v94
	v_add_f32_e32 v152, v152, v153
	v_mul_f32_e32 v153, v89, v89
	v_mul_f32_e32 v154, v91, v91
	v_fmac_f32_e32 v153, v88, v88
	v_fmac_f32_e32 v154, v90, v90
	v_add_f32_e32 v153, v153, v154
	v_add_f32_e32 v246, v152, v153
	s_waitcnt vmcnt(15)
	v_lshlrev_b32_e32 v152, 16, v180
	v_and_b32_e32 v153, 0xffff0000, v180
	v_pk_add_f32 v[84:85], v[84:85], v[152:153]
	v_lshlrev_b32_e32 v154, 16, v181
	v_and_b32_e32 v155, 0xffff0000, v181
	v_pk_add_f32 v[86:87], v[86:87], v[154:155]
	v_lshlrev_b32_e32 v156, 16, v182
	v_and_b32_e32 v157, 0xffff0000, v182
	v_pk_add_f32 v[80:81], v[80:81], v[156:157]
	v_lshlrev_b32_e32 v158, 16, v183
	v_and_b32_e32 v159, 0xffff0000, v183
	v_pk_add_f32 v[82:83], v[82:83], v[158:159]
	v_cvt_pk_bf16_f32 v240, v84, v85
	v_cvt_pk_bf16_f32 v241, v86, v87
	v_cvt_pk_bf16_f32 v242, v80, v81
	v_cvt_pk_bf16_f32 v243, v82, v83
	global_store_dwordx4 v140, v[240:243], s[2:3] offset:256
	v_mul_f32_e32 v152, v85, v85
	v_mul_f32_e32 v153, v87, v87
	v_fmac_f32_e32 v152, v84, v84
	v_fmac_f32_e32 v153, v86, v86
	v_add_f32_e32 v152, v152, v153
	v_mul_f32_e32 v153, v81, v81
	v_mul_f32_e32 v154, v83, v83
	v_fmac_f32_e32 v153, v80, v80
	v_fmac_f32_e32 v154, v82, v82
	v_add_f32_e32 v153, v153, v154
	v_add_f32_e32 v152, v152, v153
	v_add_f32_e32 v246, v246, v152
	s_waitcnt vmcnt(15)
	v_lshlrev_b32_e32 v152, 16, v184
	v_and_b32_e32 v153, 0xffff0000, v184
	v_pk_add_f32 v[76:77], v[76:77], v[152:153]
	v_lshlrev_b32_e32 v154, 16, v185
	v_and_b32_e32 v155, 0xffff0000, v185
	v_pk_add_f32 v[78:79], v[78:79], v[154:155]
	v_lshlrev_b32_e32 v156, 16, v186
	v_and_b32_e32 v157, 0xffff0000, v186
	v_pk_add_f32 v[72:73], v[72:73], v[156:157]
	v_lshlrev_b32_e32 v158, 16, v187
	v_and_b32_e32 v159, 0xffff0000, v187
	v_pk_add_f32 v[74:75], v[74:75], v[158:159]
	v_cvt_pk_bf16_f32 v236, v76, v77
	v_cvt_pk_bf16_f32 v237, v78, v79
	v_cvt_pk_bf16_f32 v238, v72, v73
	v_cvt_pk_bf16_f32 v239, v74, v75
	global_store_dwordx4 v141, v[236:239], s[2:3]
	v_mul_f32_e32 v152, v77, v77
	v_mul_f32_e32 v153, v79, v79
	v_fmac_f32_e32 v152, v76, v76
	v_fmac_f32_e32 v153, v78, v78
	v_add_f32_e32 v152, v152, v153
	v_mul_f32_e32 v153, v73, v73
	v_mul_f32_e32 v154, v75, v75
	v_fmac_f32_e32 v153, v72, v72
	v_fmac_f32_e32 v154, v74, v74
	v_add_f32_e32 v153, v153, v154
	v_add_f32_e32 v247, v152, v153
	s_waitcnt vmcnt(15)
	v_lshlrev_b32_e32 v152, 16, v188
	v_and_b32_e32 v153, 0xffff0000, v188
	v_pk_add_f32 v[68:69], v[68:69], v[152:153]
	v_lshlrev_b32_e32 v154, 16, v189
	v_and_b32_e32 v155, 0xffff0000, v189
	v_pk_add_f32 v[70:71], v[70:71], v[154:155]
	v_lshlrev_b32_e32 v156, 16, v190
	v_and_b32_e32 v157, 0xffff0000, v190
	v_pk_add_f32 v[64:65], v[64:65], v[156:157]
	v_lshlrev_b32_e32 v158, 16, v191
	v_and_b32_e32 v159, 0xffff0000, v191
	v_pk_add_f32 v[66:67], v[66:67], v[158:159]
	v_cvt_pk_bf16_f32 v240, v68, v69
	v_cvt_pk_bf16_f32 v241, v70, v71
	v_cvt_pk_bf16_f32 v242, v64, v65
	v_cvt_pk_bf16_f32 v243, v66, v67
	global_store_dwordx4 v141, v[240:243], s[2:3] offset:256
	v_mul_f32_e32 v152, v69, v69
	v_mul_f32_e32 v153, v71, v71
	v_fmac_f32_e32 v152, v68, v68
	v_fmac_f32_e32 v153, v70, v70
	v_add_f32_e32 v152, v152, v153
	v_mul_f32_e32 v153, v65, v65
	v_mul_f32_e32 v154, v67, v67
	v_fmac_f32_e32 v153, v64, v64
	v_fmac_f32_e32 v154, v66, v66
	v_add_f32_e32 v153, v153, v154
	v_add_f32_e32 v152, v152, v153
	v_add_f32_e32 v247, v247, v152
	s_waitcnt vmcnt(15)
	v_lshlrev_b32_e32 v152, 16, v192
	v_and_b32_e32 v153, 0xffff0000, v192
	v_pk_add_f32 v[60:61], v[60:61], v[152:153]
	v_lshlrev_b32_e32 v154, 16, v193
	v_and_b32_e32 v155, 0xffff0000, v193
	v_pk_add_f32 v[62:63], v[62:63], v[154:155]
	v_lshlrev_b32_e32 v156, 16, v194
	v_and_b32_e32 v157, 0xffff0000, v194
	v_pk_add_f32 v[56:57], v[56:57], v[156:157]
	v_lshlrev_b32_e32 v158, 16, v195
	v_and_b32_e32 v159, 0xffff0000, v195
	v_pk_add_f32 v[58:59], v[58:59], v[158:159]
	v_cvt_pk_bf16_f32 v236, v60, v61
	v_cvt_pk_bf16_f32 v237, v62, v63
	v_cvt_pk_bf16_f32 v238, v56, v57
	v_cvt_pk_bf16_f32 v239, v58, v59
	global_store_dwordx4 v142, v[236:239], s[2:3]
	v_mul_f32_e32 v152, v61, v61
	v_mul_f32_e32 v153, v63, v63
	v_fmac_f32_e32 v152, v60, v60
	v_fmac_f32_e32 v153, v62, v62
	v_add_f32_e32 v152, v152, v153
	v_mul_f32_e32 v153, v57, v57
	v_mul_f32_e32 v154, v59, v59
	v_fmac_f32_e32 v153, v56, v56
	v_fmac_f32_e32 v154, v58, v58
	v_add_f32_e32 v153, v153, v154
	v_add_f32_e32 v248, v152, v153
	s_waitcnt vmcnt(15)
	v_lshlrev_b32_e32 v152, 16, v196
	v_and_b32_e32 v153, 0xffff0000, v196
	v_pk_add_f32 v[52:53], v[52:53], v[152:153]
	v_lshlrev_b32_e32 v154, 16, v197
	v_and_b32_e32 v155, 0xffff0000, v197
	v_pk_add_f32 v[54:55], v[54:55], v[154:155]
	v_lshlrev_b32_e32 v156, 16, v198
	v_and_b32_e32 v157, 0xffff0000, v198
	v_pk_add_f32 v[48:49], v[48:49], v[156:157]
	v_lshlrev_b32_e32 v158, 16, v199
	v_and_b32_e32 v159, 0xffff0000, v199
	v_pk_add_f32 v[50:51], v[50:51], v[158:159]
	v_cvt_pk_bf16_f32 v240, v52, v53
	v_cvt_pk_bf16_f32 v241, v54, v55
	v_cvt_pk_bf16_f32 v242, v48, v49
	v_cvt_pk_bf16_f32 v243, v50, v51
	global_store_dwordx4 v142, v[240:243], s[2:3] offset:256
	v_mul_f32_e32 v152, v53, v53
	v_mul_f32_e32 v153, v55, v55
	v_fmac_f32_e32 v152, v52, v52
	v_fmac_f32_e32 v153, v54, v54
	v_add_f32_e32 v152, v152, v153
	v_mul_f32_e32 v153, v49, v49
	v_mul_f32_e32 v154, v51, v51
	v_fmac_f32_e32 v153, v48, v48
	v_fmac_f32_e32 v154, v50, v50
	v_add_f32_e32 v153, v153, v154
	v_add_f32_e32 v152, v152, v153
	v_add_f32_e32 v248, v248, v152
	s_waitcnt vmcnt(15)
	v_lshlrev_b32_e32 v152, 16, v200
	v_and_b32_e32 v153, 0xffff0000, v200
	v_pk_add_f32 v[44:45], v[44:45], v[152:153]
	v_lshlrev_b32_e32 v154, 16, v201
	v_and_b32_e32 v155, 0xffff0000, v201
	v_pk_add_f32 v[46:47], v[46:47], v[154:155]
	v_lshlrev_b32_e32 v156, 16, v202
	v_and_b32_e32 v157, 0xffff0000, v202
	v_pk_add_f32 v[40:41], v[40:41], v[156:157]
	v_lshlrev_b32_e32 v158, 16, v203
	v_and_b32_e32 v159, 0xffff0000, v203
	v_pk_add_f32 v[42:43], v[42:43], v[158:159]
	v_cvt_pk_bf16_f32 v236, v44, v45
	v_cvt_pk_bf16_f32 v237, v46, v47
	v_cvt_pk_bf16_f32 v238, v40, v41
	v_cvt_pk_bf16_f32 v239, v42, v43
	global_store_dwordx4 v146, v[236:239], s[2:3]
	v_mul_f32_e32 v152, v45, v45
	v_mul_f32_e32 v153, v47, v47
	v_fmac_f32_e32 v152, v44, v44
	v_fmac_f32_e32 v153, v46, v46
	v_add_f32_e32 v152, v152, v153
	v_mul_f32_e32 v153, v41, v41
	v_mul_f32_e32 v154, v43, v43
	v_fmac_f32_e32 v153, v40, v40
	v_fmac_f32_e32 v154, v42, v42
	v_add_f32_e32 v153, v153, v154
	v_add_f32_e32 v249, v152, v153
	s_waitcnt vmcnt(15)
	v_lshlrev_b32_e32 v152, 16, v212
	v_and_b32_e32 v153, 0xffff0000, v212
	v_pk_add_f32 v[36:37], v[36:37], v[152:153]
	v_lshlrev_b32_e32 v154, 16, v213
	v_and_b32_e32 v155, 0xffff0000, v213
	v_pk_add_f32 v[38:39], v[38:39], v[154:155]
	v_lshlrev_b32_e32 v156, 16, v214
	v_and_b32_e32 v157, 0xffff0000, v214
	v_pk_add_f32 v[32:33], v[32:33], v[156:157]
	v_lshlrev_b32_e32 v158, 16, v215
	v_and_b32_e32 v159, 0xffff0000, v215
	v_pk_add_f32 v[34:35], v[34:35], v[158:159]
	v_cvt_pk_bf16_f32 v240, v36, v37
	v_cvt_pk_bf16_f32 v241, v38, v39
	v_cvt_pk_bf16_f32 v242, v32, v33
	v_cvt_pk_bf16_f32 v243, v34, v35
	global_store_dwordx4 v146, v[240:243], s[2:3] offset:256
	v_mul_f32_e32 v152, v37, v37
	v_mul_f32_e32 v153, v39, v39
	v_fmac_f32_e32 v152, v36, v36
	v_fmac_f32_e32 v153, v38, v38
	v_add_f32_e32 v152, v152, v153
	v_mul_f32_e32 v153, v33, v33
	v_mul_f32_e32 v154, v35, v35
	v_fmac_f32_e32 v153, v32, v32
	v_fmac_f32_e32 v154, v34, v34
	v_add_f32_e32 v153, v153, v154
	v_add_f32_e32 v152, v152, v153
	v_add_f32_e32 v249, v249, v152
	s_waitcnt vmcnt(15)
	v_lshlrev_b32_e32 v152, 16, v220
	v_and_b32_e32 v153, 0xffff0000, v220
	v_pk_add_f32 v[28:29], v[28:29], v[152:153]
	v_lshlrev_b32_e32 v154, 16, v221
	v_and_b32_e32 v155, 0xffff0000, v221
	v_pk_add_f32 v[30:31], v[30:31], v[154:155]
	v_lshlrev_b32_e32 v156, 16, v222
	v_and_b32_e32 v157, 0xffff0000, v222
	v_pk_add_f32 v[24:25], v[24:25], v[156:157]
	v_lshlrev_b32_e32 v158, 16, v223
	v_and_b32_e32 v159, 0xffff0000, v223
	v_pk_add_f32 v[26:27], v[26:27], v[158:159]
	v_cvt_pk_bf16_f32 v236, v28, v29
	v_cvt_pk_bf16_f32 v237, v30, v31
	v_cvt_pk_bf16_f32 v238, v24, v25
	v_cvt_pk_bf16_f32 v239, v26, v27
	global_store_dwordx4 v147, v[236:239], s[2:3]
	v_mul_f32_e32 v152, v29, v29
	v_mul_f32_e32 v153, v31, v31
	v_fmac_f32_e32 v152, v28, v28
	v_fmac_f32_e32 v153, v30, v30
	v_add_f32_e32 v152, v152, v153
	v_mul_f32_e32 v153, v25, v25
	v_mul_f32_e32 v154, v27, v27
	v_fmac_f32_e32 v153, v24, v24
	v_fmac_f32_e32 v154, v26, v26
	v_add_f32_e32 v153, v153, v154
	v_add_f32_e32 v208, v152, v153
	s_waitcnt vmcnt(15)
	v_lshlrev_b32_e32 v152, 16, v224
	v_and_b32_e32 v153, 0xffff0000, v224
	v_pk_add_f32 v[20:21], v[20:21], v[152:153]
	v_lshlrev_b32_e32 v154, 16, v225
	v_and_b32_e32 v155, 0xffff0000, v225
	v_pk_add_f32 v[22:23], v[22:23], v[154:155]
	v_lshlrev_b32_e32 v156, 16, v226
	v_and_b32_e32 v157, 0xffff0000, v226
	v_pk_add_f32 v[16:17], v[16:17], v[156:157]
	v_lshlrev_b32_e32 v158, 16, v227
	v_and_b32_e32 v159, 0xffff0000, v227
	v_pk_add_f32 v[18:19], v[18:19], v[158:159]
	v_cvt_pk_bf16_f32 v240, v20, v21
	v_cvt_pk_bf16_f32 v241, v22, v23
	v_cvt_pk_bf16_f32 v242, v16, v17
	v_cvt_pk_bf16_f32 v243, v18, v19
	global_store_dwordx4 v147, v[240:243], s[2:3] offset:256
	v_mul_f32_e32 v152, v21, v21
	v_mul_f32_e32 v153, v23, v23
	v_fmac_f32_e32 v152, v20, v20
	v_fmac_f32_e32 v153, v22, v22
	v_add_f32_e32 v152, v152, v153
	v_mul_f32_e32 v153, v17, v17
	v_mul_f32_e32 v154, v19, v19
	v_fmac_f32_e32 v153, v16, v16
	v_fmac_f32_e32 v154, v18, v18
	v_add_f32_e32 v153, v153, v154
	v_add_f32_e32 v152, v152, v153
	v_add_f32_e32 v208, v208, v152
	s_waitcnt vmcnt(15)
	v_lshlrev_b32_e32 v152, 16, v228
	v_and_b32_e32 v153, 0xffff0000, v228
	v_pk_add_f32 v[12:13], v[12:13], v[152:153]
	v_lshlrev_b32_e32 v154, 16, v229
	v_and_b32_e32 v155, 0xffff0000, v229
	v_pk_add_f32 v[14:15], v[14:15], v[154:155]
	v_lshlrev_b32_e32 v156, 16, v230
	v_and_b32_e32 v157, 0xffff0000, v230
	v_pk_add_f32 v[8:9], v[8:9], v[156:157]
	v_lshlrev_b32_e32 v158, 16, v231
	v_and_b32_e32 v159, 0xffff0000, v231
	v_pk_add_f32 v[10:11], v[10:11], v[158:159]
	v_cvt_pk_bf16_f32 v236, v12, v13
	v_cvt_pk_bf16_f32 v237, v14, v15
	v_cvt_pk_bf16_f32 v238, v8, v9
	v_cvt_pk_bf16_f32 v239, v10, v11
	global_store_dwordx4 v219, v[236:239], s[2:3]
	v_mul_f32_e32 v152, v13, v13
	v_mul_f32_e32 v153, v15, v15
	v_fmac_f32_e32 v152, v12, v12
	v_fmac_f32_e32 v153, v14, v14
	v_add_f32_e32 v152, v152, v153
	v_mul_f32_e32 v153, v9, v9
	v_mul_f32_e32 v154, v11, v11
	v_fmac_f32_e32 v153, v8, v8
	v_fmac_f32_e32 v154, v10, v10
	v_add_f32_e32 v153, v153, v154
	v_add_f32_e32 v209, v152, v153
	s_waitcnt vmcnt(15)
	v_lshlrev_b32_e32 v152, 16, v232
	v_and_b32_e32 v153, 0xffff0000, v232
	v_pk_add_f32 v[4:5], v[4:5], v[152:153]
	v_lshlrev_b32_e32 v154, 16, v233
	v_and_b32_e32 v155, 0xffff0000, v233
	v_pk_add_f32 v[6:7], v[6:7], v[154:155]
	v_lshlrev_b32_e32 v156, 16, v234
	v_and_b32_e32 v157, 0xffff0000, v234
	v_pk_add_f32 v[0:1], v[0:1], v[156:157]
	v_lshlrev_b32_e32 v158, 16, v235
	v_and_b32_e32 v159, 0xffff0000, v235
	v_pk_add_f32 v[2:3], v[2:3], v[158:159]
	v_cvt_pk_bf16_f32 v240, v4, v5
	v_cvt_pk_bf16_f32 v241, v6, v7
	v_cvt_pk_bf16_f32 v242, v0, v1
	v_cvt_pk_bf16_f32 v243, v2, v3
	global_store_dwordx4 v219, v[240:243], s[2:3] offset:256
	v_mul_f32_e32 v152, v5, v5
	v_mul_f32_e32 v153, v7, v7
	v_fmac_f32_e32 v152, v4, v4
	v_fmac_f32_e32 v153, v6, v6
	v_add_f32_e32 v152, v152, v153
	v_mul_f32_e32 v153, v1, v1
	v_mul_f32_e32 v154, v3, v3
	v_fmac_f32_e32 v153, v0, v0
	v_fmac_f32_e32 v154, v2, v2
	v_add_f32_e32 v153, v153, v154
	v_add_f32_e32 v152, v152, v153
	v_add_f32_e32 v209, v209, v152
	ds_bpermute_b32 v152, v217, v244
	ds_bpermute_b32 v153, v217, v245
	ds_bpermute_b32 v154, v217, v246
	ds_bpermute_b32 v155, v217, v247
	ds_bpermute_b32 v156, v217, v248
	ds_bpermute_b32 v157, v217, v249
	ds_bpermute_b32 v158, v217, v208
	ds_bpermute_b32 v159, v217, v209
	s_waitcnt lgkmcnt(0)
	v_add_f32_e32 v244, v244, v152
	v_add_f32_e32 v245, v245, v153
	v_add_f32_e32 v246, v246, v154
	v_add_f32_e32 v247, v247, v155
	v_add_f32_e32 v248, v248, v156
	v_add_f32_e32 v249, v249, v157
	v_add_f32_e32 v208, v208, v158
	v_add_f32_e32 v209, v209, v159
	ds_bpermute_b32 v152, v218, v244
	ds_bpermute_b32 v153, v218, v245
	ds_bpermute_b32 v154, v218, v246
	ds_bpermute_b32 v155, v218, v247
	ds_bpermute_b32 v156, v218, v248
	ds_bpermute_b32 v157, v218, v249
	ds_bpermute_b32 v158, v218, v208
	ds_bpermute_b32 v159, v218, v209
	s_waitcnt lgkmcnt(0)
	v_add_f32_e32 v244, v244, v152
	v_add_f32_e32 v245, v245, v153
	v_add_f32_e32 v246, v246, v154
	v_add_f32_e32 v247, v247, v155
	v_add_f32_e32 v248, v248, v156
	v_add_f32_e32 v249, v249, v157
	v_add_f32_e32 v208, v208, v158
	v_add_f32_e32 v209, v209, v159
	v_add_u32_e32 v204, 0x2000, v150
	v_cmp_eq_u32_e64 s[18:19], 0, v151
	s_nop 3
	s_and_saveexec_b64 s[20:21], s[18:19]
	global_store_dword v150, v244, s[6:7]
	global_store_dword v150, v245, s[6:7] offset:1024
	global_store_dword v150, v246, s[6:7] offset:2048
	global_store_dword v150, v247, s[6:7] offset:3072
	global_store_dword v204, v248, s[6:7]
	global_store_dword v204, v249, s[6:7] offset:1024
	global_store_dword v204, v208, s[6:7] offset:2048
	global_store_dword v204, v209, s[6:7] offset:3072
